# first grid barrier: the sixteen per-XCD census counter loads are issued together (one base register plus offsets) instead of ten serialized round trips; on top of the flat-release + arrival-invalidate
# speedup vs baseline: 1.0132x; 1.0132x over previous
; __device__ __forceinline__ unsigned xb_ld(unsigned* p)              { return __hip_atomic_load(p, __ATOMIC_RELAXED, __HIP_MEMORY_SCOPE_AGENT); }
; __device__ __forceinline__ void xcd_barrier_complete(unsigned* bar, unsigned x, unsigned& nloc, unsigned& nx) {
;     ...
;     for (;;) {
;         sum = 0u; cnt = 0u; mine = 0u;
; #pragma unroll
;         for (unsigned j = 0; j < 16; ++j) { const unsigned c = xb_ld(&bar[XB_XCNT(j)]); sum += c; cnt += (c > 0u) ? 1u : 0u; mine = (j == x) ? c : mine; }
;         if (sum == G) break;
;         __builtin_amdgcn_s_sleep(1);
;         if ((++sp & 255u) == 0u) { if (xb_ld(&bar[XB_TMO])) break; if (sp > XB_SPIN_CAP) { atomicAdd(&bar[XB_TMO], 1u); break; } }
.LBB0_109:
	s_waitcnt lgkmcnt(0)
	global_load_dword v1, v161, s[56:57] offset:-3840 sc1
	global_load_dword v0, v161, s[56:57] offset:-3584 sc1
	global_load_dword v2, v161, s[56:57] offset:-3328 sc1
	global_load_dword v3, v161, s[56:57] offset:-3072 sc1
	global_load_dword v4, v161, s[56:57] offset:-2816 sc1
	global_load_dword v5, v161, s[56:57] offset:-2560 sc1
	global_load_dword v6, v161, s[56:57] offset:-2304 sc1
	global_load_dword v7, v161, s[56:57] offset:-2048 sc1
	global_load_dword v8, v161, s[56:57] offset:-1792 sc1
	global_load_dword v9, v161, s[56:57] offset:-1536 sc1
	global_load_dword v10, v161, s[56:57] offset:-1280 sc1
	global_load_dword v11, v161, s[56:57] offset:-1024 sc1
	global_load_dword v12, v161, s[56:57] offset:-768 sc1
	global_load_dword v13, v161, s[56:57] offset:-512 sc1
	global_load_dword v14, v161, s[56:57] offset:-256 sc1
	global_load_dword v15, v161, s[56:57] sc1
	s_mov_b64 s[6:7], -1
	s_mov_b64 s[4:5], -1
	s_waitcnt vmcnt(0)
	v_add_u32_e32 v16, v0, v1
	v_add_u32_e32 v16, v16, v2
	v_add_u32_e32 v16, v16, v3
	v_add_u32_e32 v16, v16, v4
	v_add_u32_e32 v16, v16, v5
	v_add_u32_e32 v16, v16, v6
	v_add_u32_e32 v16, v16, v7
	v_add_u32_e32 v16, v16, v8
	v_add_u32_e32 v16, v16, v9
	v_add_u32_e32 v16, v16, v10
	v_add_u32_e32 v16, v16, v11
	v_add_u32_e32 v16, v16, v12
	v_add_u32_e32 v16, v16, v13
	v_add_u32_e32 v16, v16, v14
	v_add_u32_e32 v16, v16, v15
	v_cmp_eq_u32_e32 vcc, s88, v16
	s_cbranch_vccnz .LBB0_108
	s_and_b32 s4, s11, 0xff
	s_cmp_eq_u32 s4, 0
	s_mov_b64 s[4:5], -1
	s_mov_b64 s[8:9], -1
	s_sleep 1
	s_cbranch_scc0 .LBB0_113
	global_load_dword v16, v161, s[74:75] sc1
	s_waitcnt vmcnt(0)
	v_cmp_eq_u32_e32 vcc, 0, v16
	s_cbranch_vccnz .LBB0_115
	s_mov_b64 s[8:9], 0
